# k2 + MLA loop: V fragment reads hoisted after QK MFMAs + split softmax; band loop: split softmax (PV of first key half before exp of second half)
# speedup vs baseline: 1.0035x; 1.0035x over previous
; __device__ __forceinline__ unsigned cvtpk(float lo, float hi) { return __builtin_bit_cast(unsigned, __builtin_convertvector(f32x2_cv{lo, hi}, bf16x2_cv)); }
; __device__ __forceinline__ float dot2bf(unsigned w, unsigned x, float acc) { return __builtin_amdgcn_fdot2_f32_bf16(__builtin_bit_cast(bf16x2_t, w), __builtin_bit_cast(bf16x2_t, x), acc, false); }
; template <int DK, int MODE, bool OUTF32> ...
;     ...
;             for (int r = 0; r < 16; ++r) p[r] = __builtin_amdgcn_exp2f((MODE == 2) ? fmaf(p[r], sc2, -m) : (p[r] - m));
;             bf16x8 pb0, pb1;
;             { const unsigned w0 = cvtpk(p[0], p[1]), w1 = cvtpk(p[2], p[3]), w2 = cvtpk(p[4], p[5]), w3 = cvtpk(p[6], p[7]);
;               const uint4 u = make_uint4(w0, w1, w2, w3); pb0 = *reinterpret_cast<const bf16x8*>(&u); }
;             { const unsigned w0 = cvtpk(p[8], p[9]), w1 = cvtpk(p[10], p[11]), w2 = cvtpk(p[12], p[13]), w3 = cvtpk(p[14], p[15]);
;               const uint4 u = make_uint4(w0, w1, w2, w3); pb1 = *reinterpret_cast<const bf16x8*>(&u); }
;             {
;                 const uint4 ua = *reinterpret_cast<const uint4*>(&pb0), ub = *reinterpret_cast<const uint4*>(&pb1);
;                 float ps = 0.f, ps2 = 0.f;
;                 ps = dot2bf(ua.x, 0x3f803f80u, ps); ps2 = dot2bf(ua.y, 0x3f803f80u, ps2); ps = dot2bf(ua.z, 0x3f803f80u, ps); ps2 = dot2bf(ua.w, 0x3f803f80u, ps2);
;                 ps = dot2bf(ub.x, 0x3f803f80u, ps); ps2 = dot2bf(ub.y, 0x3f803f80u, ps2); ps = dot2bf(ub.z, 0x3f803f80u, ps); ps2 = dot2bf(ub.w, 0x3f803f80u, ps2);
;                 l += ps + ps2;
;             }
;             if (HOISTK && !HOISTV) A_VREADS(0, 4);
;             if (HOISTK) __builtin_amdgcn_sched_barrier(0);
; #pragma unroll
;             for (int db = 0; db < 4; ++db) {
;                 if (!HOISTK) { A_VREADS(db, db + 1); }
;                 o[db] = __builtin_amdgcn_mfma_f32_32x32x16_bf16(vf[2 * db], pb0, o[db], 0, 0, 0);
;                 o[db] = __builtin_amdgcn_mfma_f32_32x32x16_bf16(vf[2 * db + 1], pb1, o[db], 0, 0, 0);
;             }
.LBB0_260:
	v_sub_f32_e32 v68, v68, v223
	v_sub_f32_e32 v69, v69, v223
	v_sub_f32_e32 v70, v70, v223
	v_sub_f32_e32 v71, v71, v223
	v_sub_f32_e32 v72, v72, v223
	v_sub_f32_e32 v73, v73, v223
	v_sub_f32_e32 v74, v74, v223
	v_sub_f32_e32 v75, v75, v223
	v_exp_f32_e32 v68, v68
	v_exp_f32_e32 v69, v69
	v_exp_f32_e32 v70, v70
	v_exp_f32_e32 v71, v71
	v_exp_f32_e32 v72, v72
	v_exp_f32_e32 v73, v73
	v_exp_f32_e32 v74, v74
	v_exp_f32_e32 v75, v75
	v_cvt_pk_bf16_f32 v68, v68, v69
	v_cvt_pk_bf16_f32 v69, v70, v71
	v_cvt_pk_bf16_f32 v70, v72, v73
	v_cvt_pk_bf16_f32 v71, v74, v75
	v_mov_b32_e32 v84, 0
	v_mov_b32_e32 v85, 0
	v_dot2c_f32_bf16_e32 v84, 0x3f803f80, v68
	v_dot2c_f32_bf16_e32 v85, 0x3f803f80, v69
	v_dot2c_f32_bf16_e32 v84, 0x3f803f80, v70
	v_dot2c_f32_bf16_e32 v85, 0x3f803f80, v71
	s_waitcnt lgkmcnt(7)
	v_mfma_f32_32x32x16_bf16 v[36:51], v[148:151], v[68:71], v[36:51]
	s_waitcnt lgkmcnt(5)
	v_mfma_f32_32x32x16_bf16 v[20:35], v[156:159], v[68:71], v[20:35]
	s_waitcnt lgkmcnt(3)
	v_mfma_f32_32x32x16_bf16 v[52:67], v[164:167], v[68:71], v[52:67]
	s_waitcnt lgkmcnt(1)
	v_mfma_f32_32x32x16_bf16 v[4:19], v[176:179], v[68:71], v[4:19]
	v_sub_f32_e32 v76, v76, v223
	v_sub_f32_e32 v77, v77, v223
	v_sub_f32_e32 v78, v78, v223
	v_sub_f32_e32 v79, v79, v223
	v_sub_f32_e32 v80, v80, v223
	v_sub_f32_e32 v81, v81, v223
	v_sub_f32_e32 v82, v82, v223
	v_sub_f32_e32 v83, v83, v223
	v_exp_f32_e32 v76, v76
	v_exp_f32_e32 v77, v77
	v_exp_f32_e32 v78, v78
	v_exp_f32_e32 v79, v79
	v_exp_f32_e32 v80, v80
	v_exp_f32_e32 v81, v81
	v_exp_f32_e32 v82, v82
	v_exp_f32_e32 v83, v83
	v_cvt_pk_bf16_f32 v72, v76, v77
	v_cvt_pk_bf16_f32 v73, v78, v79
	v_cvt_pk_bf16_f32 v74, v80, v81
	v_cvt_pk_bf16_f32 v75, v82, v83
	v_dot2c_f32_bf16_e32 v84, 0x3f803f80, v72
	v_dot2c_f32_bf16_e32 v85, 0x3f803f80, v73
	v_dot2c_f32_bf16_e32 v84, 0x3f803f80, v74
	v_dot2c_f32_bf16_e32 v85, 0x3f803f80, v75
	s_nop 2
	v_add_f32_e32 v84, v84, v85
	v_mfma_f32_32x32x16_bf16 v[36:51], v[152:155], v[72:75], v[36:51]
	v_add_f32_e32 v210, v210, v84
	v_mfma_f32_32x32x16_bf16 v[20:35], v[160:163], v[72:75], v[20:35]
	v_mfma_f32_32x32x16_bf16 v[52:67], v[168:171], v[72:75], v[52:67]
	s_waitcnt lgkmcnt(0)
	v_mfma_f32_32x32x16_bf16 v[4:19], v[172:175], v[72:75], v[4:19]

; __device__ __forceinline__ unsigned cvtpk(float lo, float hi) { return __builtin_bit_cast(unsigned, __builtin_convertvector(f32x2_cv{lo, hi}, bf16x2_cv)); }
; __device__ __forceinline__ float dot2bf(unsigned w, unsigned x, float acc) { return __builtin_amdgcn_fdot2_f32_bf16(__builtin_bit_cast(bf16x2_t, w), __builtin_bit_cast(bf16x2_t, x), acc, false); }
; template <int DK, int MODE, bool OUTF32> ...
;     ...
;             for (int r = 0; r < 16; ++r) p[r] = __builtin_amdgcn_exp2f((MODE == 2) ? fmaf(p[r], sc2, -m) : (p[r] - m));
;             bf16x8 pb0, pb1;
;             { const unsigned w0 = cvtpk(p[0], p[1]), w1 = cvtpk(p[2], p[3]), w2 = cvtpk(p[4], p[5]), w3 = cvtpk(p[6], p[7]);
;               const uint4 u = make_uint4(w0, w1, w2, w3); pb0 = *reinterpret_cast<const bf16x8*>(&u); }
;             { const unsigned w0 = cvtpk(p[8], p[9]), w1 = cvtpk(p[10], p[11]), w2 = cvtpk(p[12], p[13]), w3 = cvtpk(p[14], p[15]);
;               const uint4 u = make_uint4(w0, w1, w2, w3); pb1 = *reinterpret_cast<const bf16x8*>(&u); }
;             {
;                 const uint4 ua = *reinterpret_cast<const uint4*>(&pb0), ub = *reinterpret_cast<const uint4*>(&pb1);
;                 float ps = 0.f, ps2 = 0.f;
;                 ps = dot2bf(ua.x, 0x3f803f80u, ps); ps2 = dot2bf(ua.y, 0x3f803f80u, ps2); ps = dot2bf(ua.z, 0x3f803f80u, ps); ps2 = dot2bf(ua.w, 0x3f803f80u, ps2);
;                 ps = dot2bf(ub.x, 0x3f803f80u, ps); ps2 = dot2bf(ub.y, 0x3f803f80u, ps2); ps = dot2bf(ub.z, 0x3f803f80u, ps); ps2 = dot2bf(ub.w, 0x3f803f80u, ps2);
;                 l += ps + ps2;
;             }
;             if (HOISTK && !HOISTV) A_VREADS(0, 4);
;             if (HOISTK) __builtin_amdgcn_sched_barrier(0);
; #pragma unroll
;             for (int db = 0; db < 4; ++db) {
;                 if (!HOISTK) { A_VREADS(db, db + 1); }
;                 o[db] = __builtin_amdgcn_mfma_f32_32x32x16_bf16(vf[2 * db], pb0, o[db], 0, 0, 0);
;                 o[db] = __builtin_amdgcn_mfma_f32_32x32x16_bf16(vf[2 * db + 1], pb1, o[db], 0, 0, 0);
;             }
.LBB0_957:
	v_fma_f32 v82, v82, s74, -v173
	v_fma_f32 v83, v83, s74, -v173
	v_fma_f32 v84, v84, s74, -v173
	v_fma_f32 v85, v85, s74, -v173
	v_fma_f32 v86, v86, s74, -v173
	v_fma_f32 v87, v87, s74, -v173
	v_fma_f32 v88, v88, s74, -v173
	v_fma_f32 v89, v89, s74, -v173
	v_exp_f32_e32 v82, v82
	v_exp_f32_e32 v83, v83
	v_exp_f32_e32 v84, v84
	v_exp_f32_e32 v85, v85
	v_exp_f32_e32 v86, v86
	v_exp_f32_e32 v87, v87
	v_exp_f32_e32 v88, v88
	v_exp_f32_e32 v89, v89
	v_cvt_pk_bf16_f32 v82, v82, v83
	v_cvt_pk_bf16_f32 v83, v84, v85
	v_cvt_pk_bf16_f32 v84, v86, v87
	v_cvt_pk_bf16_f32 v85, v88, v89
	v_mov_b32_e32 v2, 0
	v_mov_b32_e32 v16, 0
	v_dot2c_f32_bf16_e32 v2, 0x3f803f80, v82
	v_dot2c_f32_bf16_e32 v16, 0x3f803f80, v83
	v_dot2c_f32_bf16_e32 v2, 0x3f803f80, v84
	v_dot2c_f32_bf16_e32 v16, 0x3f803f80, v85
	s_waitcnt lgkmcnt(7)
	v_mfma_f32_32x32x16_bf16 v[66:81], v[220:223], v[82:85], v[66:81]
	s_waitcnt lgkmcnt(5)
	v_mfma_f32_32x32x16_bf16 v[34:49], v[186:189], v[82:85], v[34:49]
	s_waitcnt lgkmcnt(3)
	v_mfma_f32_32x32x16_bf16 v[50:65], v[194:197], v[82:85], v[50:65]
	s_waitcnt lgkmcnt(1)
	v_mfma_f32_32x32x16_bf16 v[18:33], v[212:215], v[82:85], v[18:33]
	v_fma_f32 v90, v90, s74, -v173
	v_fma_f32 v91, v91, s74, -v173
	v_fma_f32 v92, v92, s74, -v173
	v_fma_f32 v93, v93, s74, -v173
	v_fma_f32 v94, v94, s74, -v173
	v_fma_f32 v95, v95, s74, -v173
	v_fma_f32 v96, v96, s74, -v173
	v_fma_f32 v97, v97, s74, -v173
	v_exp_f32_e32 v90, v90
	v_exp_f32_e32 v91, v91
	v_exp_f32_e32 v92, v92
	v_exp_f32_e32 v93, v93
	v_exp_f32_e32 v94, v94
	v_exp_f32_e32 v95, v95
	v_exp_f32_e32 v96, v96
	v_exp_f32_e32 v97, v97
	v_cvt_pk_bf16_f32 v86, v90, v91
	v_cvt_pk_bf16_f32 v87, v92, v93
	v_cvt_pk_bf16_f32 v88, v94, v95
	v_cvt_pk_bf16_f32 v89, v96, v97
	v_dot2c_f32_bf16_e32 v2, 0x3f803f80, v86
	v_dot2c_f32_bf16_e32 v16, 0x3f803f80, v87
	v_dot2c_f32_bf16_e32 v2, 0x3f803f80, v88
	v_dot2c_f32_bf16_e32 v16, 0x3f803f80, v89
	s_nop 2
	v_add_f32_e32 v2, v2, v16
	v_mfma_f32_32x32x16_bf16 v[66:81], v[224:227], v[86:89], v[66:81]
	v_add_f32_e32 v171, v171, v2
	v_mfma_f32_32x32x16_bf16 v[34:49], v[190:193], v[86:89], v[34:49]
	v_mfma_f32_32x32x16_bf16 v[50:65], v[208:211], v[86:89], v[50:65]
	s_waitcnt lgkmcnt(0)
	v_mfma_f32_32x32x16_bf16 v[18:33], v[216:219], v[86:89], v[18:33]

; template <int DK, int MODE, bool OUTF32> ...
;     ...
;         if (act) {
;             f32x16 p;
; #pragma unroll
;             for (int r = 0; r < 16; ++r) p[r] = 0.f;
;             const unsigned char* kb = a_lds + cur * KBUF + (32 * kh + c) * KP + hi * 16;
;             constexpr bool HOISTK = true;
;             bf16x8 kf[NKS];
;             if (HOISTK) {
; #pragma unroll
;                 for (int s = 0; s < NKS; ++s) kf[s] = *(const bf16x8*)(kb + s * 32);
;             }
;             const unsigned char* vb = a_lds + OFF_V + cur * VBUF + c * VP + (32 * kh + 4 * hi) * 2;
;             bf16x8 vf[8];
;     ...
;             constexpr bool HOISTV = (DK == 128) && (MODE == 2 || MODE == 1);
;             if (HOISTV) A_VREADS(0, 3);
;             if (HOISTK) __builtin_amdgcn_sched_barrier(0);
; #pragma unroll
;             for (int s = 0; s < NKS; ++s) p = __builtin_amdgcn_mfma_f32_32x32x16_bf16(HOISTK ? kf[s] : *(const bf16x8*)(kb + s * 32), qf[s], p, 0, 0, 0);
;             if (HOISTV) { A_VREADS(3, 4); __builtin_amdgcn_sched_barrier(0); }
;             if (MODE == 0) {
;                 const float* ckp = (const float*)(a_lds + OFF_CK + cur * 256) + 32 * kh + 4 * hi;
; #pragma unroll
;                 for (int g = 0; g < 4; ++g) {
;                     const float4 ck = *(const float4*)(ckp + 8 * g);
;                     p[4 * g + 0] = fmaf(p[4 * g + 0], sc2, cq - ck.x); p[4 * g + 1] = fmaf(p[4 * g + 1], sc2, cq - ck.y);
;                     p[4 * g + 2] = fmaf(p[4 * g + 2], sc2, cq - ck.z); p[4 * g + 3] = fmaf(p[4 * g + 3], sc2, cq - ck.w);
;                 }
;                 if (64 * t + 32 * kh + 31 > qw0) {
;                     const int kbase = 64 * t + 32 * kh + 4 * hi;
; #pragma unroll
;                     for (int r = 0; r < 16; ++r) if (kbase + (r & 3) + 8 * (r >> 2) > qrow) p[r] = NEGINF;
;                 }
;             } else if (MODE == 1) {
;                 const float* rb = (const float*)(a_lds + OFF_RB);
;                 if (t <= cw - 3) {
;                     const float bb = rb[256];
; #pragma unroll
;                     for (int r = 0; r < 16; ++r) p[r] = fmaf(p[r], sc2, bb);
;                 } else {
;                     const int kbase = 64 * t + 32 * kh + 4 * hi;
; #pragma unroll
.LBB0_959:
	s_and_b32 s13, s12, 1
	v_cmp_le_i32_e32 vcc, s12, v179
	s_and_saveexec_b64 s[50:51], vcc
	s_cbranch_execz .Lmla_inact
	s_mul_i32 s14, s13, 0x6400
	v_add_u32_e32 v2, s14, v176
	ds_read_b128 v[82:85], v2
	ds_read_b128 v[186:189], v2 offset:32
	ds_read_b128 v[190:193], v2 offset:64
	ds_read_b128 v[194:197], v2 offset:96
	ds_read_b128 v[208:211], v2 offset:128
	ds_read_b128 v[212:215], v2 offset:160
	ds_read_b128 v[216:219], v2 offset:192
	ds_read_b128 v[220:223], v2 offset:224
	ds_read_b128 v[224:227], v2 offset:256
	ds_read_b128 v[228:231], v2 offset:288
	ds_read_b128 v[232:235], v2 offset:320
	ds_read_b128 v[236:239], v2 offset:352
	v_add_co_u32_e32 v246, vcc, 0xfff80000, v162
	v_lshl_add_u64 v[240:241], v[158:159], 0, v[164:165]
	v_lshl_add_u64 v[242:243], v[158:159], 0, v[168:169]
	v_lshl_add_u64 v[244:245], v[158:159], 0, v[166:167]
	v_addc_co_u32_e32 v247, vcc, -1, v163, vcc
	global_load_dwordx4 v[12:15], v[240:241], off
	global_load_dwordx4 v[4:7], v[242:243], off
	global_load_dwordx4 v[8:11], v[244:245], off
	global_load_dwordx4 v[150:153], v[246:247], off
	global_load_dwordx4 v[146:149], v[162:163], off
	s_waitcnt lgkmcnt(11)
	v_mfma_f32_32x32x16_bf16 v[82:97], v[82:85], v[142:145], 0
	s_mov_b32 s14, 0x41000000
	s_waitcnt lgkmcnt(10)
	v_mfma_f32_32x32x16_bf16 v[82:97], v[186:189], v[138:141], v[82:97]
	s_waitcnt lgkmcnt(9)
	v_mfma_f32_32x32x16_bf16 v[82:97], v[190:193], v[134:137], v[82:97]
	s_waitcnt lgkmcnt(8)
	v_mfma_f32_32x32x16_bf16 v[82:97], v[194:197], v[130:133], v[82:97]
	s_waitcnt lgkmcnt(7)
	v_mfma_f32_32x32x16_bf16 v[82:97], v[208:211], v[126:129], v[82:97]
	s_waitcnt lgkmcnt(6)
	v_mfma_f32_32x32x16_bf16 v[82:97], v[212:215], v[122:125], v[82:97]
	s_waitcnt lgkmcnt(5)
	v_mfma_f32_32x32x16_bf16 v[82:97], v[216:219], v[118:121], v[82:97]
	s_waitcnt lgkmcnt(4)
	v_mfma_f32_32x32x16_bf16 v[82:97], v[220:223], v[114:117], v[82:97]
	s_waitcnt lgkmcnt(3)
	v_mfma_f32_32x32x16_bf16 v[82:97], v[224:227], v[110:113], v[82:97]
	s_waitcnt lgkmcnt(2)
	v_mfma_f32_32x32x16_bf16 v[82:97], v[228:231], v[106:109], v[82:97]
	s_waitcnt lgkmcnt(1)
	v_mfma_f32_32x32x16_bf16 v[82:97], v[232:235], v[102:105], v[82:97]
	s_waitcnt lgkmcnt(0)
	v_mfma_f32_32x32x16_bf16 v[82:97], v[236:239], v[98:101], v[82:97]
	s_mul_i32 s101, s13, 0x4400
	v_add_u32_e32 v250, s101, v174
	v_add_u32_e32 v251, 0xc800, v250
	v_add_u32_e32 v252, 0xd800, v250
	v_add_u32_e32 v253, 0xe800, v250
	v_add_u32_e32 v250, 0xf800, v250
	ds_read2_b64 v[220:223], v251 offset1:2
	ds_read2_b64 v[224:227], v251 offset0:4 offset1:6
	ds_read2_b64 v[186:189], v252 offset0:32 offset1:34
	ds_read2_b64 v[190:193], v252 offset0:36 offset1:38
	ds_read2_b64 v[194:197], v253 offset0:64 offset1:66
	ds_read2_b64 v[208:211], v253 offset0:68 offset1:70
	ds_read2_b64 v[212:215], v250 offset0:96 offset1:98
	ds_read2_b64 v[216:219], v250 offset0:100 offset1:102
	s_nop 1
	v_max_f32_e32 v2, v83, v83
	v_max_f32_e32 v16, v82, v82
	v_max_f32_e32 v2, v16, v2
	v_max3_f32 v2, v2, v84, v85
	v_max3_f32 v2, v2, v86, v87
	v_max3_f32 v2, v2, v88, v89
	v_max3_f32 v2, v2, v90, v91
	v_max3_f32 v2, v2, v92, v93
	v_max3_f32 v2, v2, v94, v95
	v_max3_f32 v2, v2, v96, v97
	v_mul_f32_e32 v2, 0x3dd53b94, v2
	v_mov_b32_e32 v16, v2
	s_nop 1
	v_permlane32_swap_b32_e32 v2, v16
	v_max_f32_e32 v16, v16, v16
	v_max_f32_e32 v2, v2, v2
	v_max_f32_e32 v2, v2, v16
	v_sub_f32_e32 v16, v2, v173
	v_cmp_ge_f32_e32 vcc, s14, v16
	s_cmp_eq_u64 vcc, exec
	s_cbranch_scc1 .LBB0_957
	v_max_f32_e32 v2, v2, v2
	v_max_f32_e32 v16, v173, v173
	v_max_f32_e32 v16, v16, v2
	v_sub_f32_e32 v2, v173, v16
	v_exp_f32_e32 v2, v2
	v_mov_b32_e32 v173, v16
	v_pk_mul_f32 v[80:81], v[80:81], v[2:3] op_sel_hi:[1,0]
	v_pk_mul_f32 v[78:79], v[78:79], v[2:3] op_sel_hi:[1,0]
	v_pk_mul_f32 v[76:77], v[76:77], v[2:3] op_sel_hi:[1,0]
	v_pk_mul_f32 v[74:75], v[74:75], v[2:3] op_sel_hi:[1,0]
	v_pk_mul_f32 v[72:73], v[72:73], v[2:3] op_sel_hi:[1,0]
	v_pk_mul_f32 v[70:71], v[70:71], v[2:3] op_sel_hi:[1,0]
	v_pk_mul_f32 v[68:69], v[68:69], v[2:3] op_sel_hi:[1,0]
	v_pk_mul_f32 v[66:67], v[66:67], v[2:3] op_sel_hi:[1,0]
	v_pk_mul_f32 v[48:49], v[48:49], v[2:3] op_sel_hi:[1,0]
	v_pk_mul_f32 v[46:47], v[46:47], v[2:3] op_sel_hi:[1,0]
	v_pk_mul_f32 v[44:45], v[44:45], v[2:3] op_sel_hi:[1,0]
	v_pk_mul_f32 v[42:43], v[42:43], v[2:3] op_sel_hi:[1,0]
	v_pk_mul_f32 v[40:41], v[40:41], v[2:3] op_sel_hi:[1,0]
	v_pk_mul_f32 v[38:39], v[38:39], v[2:3] op_sel_hi:[1,0]
	v_pk_mul_f32 v[36:37], v[36:37], v[2:3] op_sel_hi:[1,0]
	v_pk_mul_f32 v[34:35], v[34:35], v[2:3] op_sel_hi:[1,0]
	v_pk_mul_f32 v[64:65], v[64:65], v[2:3] op_sel_hi:[1,0]
	v_pk_mul_f32 v[62:63], v[62:63], v[2:3] op_sel_hi:[1,0]
	v_pk_mul_f32 v[60:61], v[60:61], v[2:3] op_sel_hi:[1,0]
	v_pk_mul_f32 v[58:59], v[58:59], v[2:3] op_sel_hi:[1,0]
	v_pk_mul_f32 v[56:57], v[56:57], v[2:3] op_sel_hi:[1,0]
	v_pk_mul_f32 v[54:55], v[54:55], v[2:3] op_sel_hi:[1,0]
	v_pk_mul_f32 v[52:53], v[52:53], v[2:3] op_sel_hi:[1,0]
	v_pk_mul_f32 v[50:51], v[50:51], v[2:3] op_sel_hi:[1,0]
	v_pk_mul_f32 v[32:33], v[32:33], v[2:3] op_sel_hi:[1,0]
	v_pk_mul_f32 v[30:31], v[30:31], v[2:3] op_sel_hi:[1,0]
	v_pk_mul_f32 v[28:29], v[28:29], v[2:3] op_sel_hi:[1,0]
	v_pk_mul_f32 v[26:27], v[26:27], v[2:3] op_sel_hi:[1,0]
	v_pk_mul_f32 v[24:25], v[24:25], v[2:3] op_sel_hi:[1,0]
	v_pk_mul_f32 v[22:23], v[22:23], v[2:3] op_sel_hi:[1,0]
	v_pk_mul_f32 v[20:21], v[20:21], v[2:3] op_sel_hi:[1,0]
	v_pk_mul_f32 v[18:19], v[18:19], v[2:3] op_sel_hi:[1,0]
	v_mul_f32_e32 v171, v171, v2
	s_branch .LBB0_957
